# final rmsnorm phase: all 10 loads of an output row issued up front (was 5 dependent round trips per iteration)
# speedup vs baseline: 1.0028x; 1.0028x over previous
.LBB0_56:
	v_mov_b32_e32 v16, v210
	v_mov_b32_e32 v2, v210
	s_load_dwordx2 s[0:1], s[82:83], 0x118
	v_bfe_u32 v2, v2, 6, 2
	v_add_u32_e32 v12, v3, v2
	v_ashrrev_i32_e32 v2, 11, v1
	v_and_b32_e32 v4, 0x1fff, v12
	v_add_u32_e32 v196, 0x80, v4
	v_mul_hi_i32_i24_e32 v5, 0x2080, v2
	v_mul_i32_i24_e32 v4, 0x2080, v2
	v_lshl_add_u64 v[14:15], v[4:5], 0, v[196:197]
	v_lshlrev_b64 v[4:5], 5, v[14:15]
	s_waitcnt lgkmcnt(0)
	v_lshl_add_u64 v[8:9], s[0:1], 0, v[4:5]
	global_load_dwordx4 v[4:7], v[8:9], off offset:16
	s_nop 0
	global_load_dwordx4 v[8:11], v[8:9], off
	s_load_dwordx4 s[0:3], s[82:83], 0x98
	s_load_dwordx2 s[6:7], s[82:83], 0xa8
	v_ashrrev_i32_e32 v13, 31, v12
	s_add_i32 s4, s4, s5
	v_add_u32_e32 v1, s8, v1
	s_cmpk_gt_i32 s4, 0x7ff
	v_lshlrev_b32_e32 v17, 4, v16
	v_and_b32_e32 v196, 0x3f0, v17
	v_lshlrev_b64 v[52:53], 12, v[14:15]
	s_waitcnt lgkmcnt(0)
	v_lshl_add_u64 v[52:53], s[6:7], 0, v[52:53]
	v_lshl_add_u64 v[14:15], v[52:53], 0, v[196:197]
	global_load_dwordx4 v[20:23], v[14:15], off
	global_load_dwordx4 v[36:39], v196, s[0:1]
	global_load_dwordx4 v[24:27], v[14:15], off offset:1024
	global_load_dwordx4 v[40:43], v196, s[0:1] offset:1024
	global_load_dwordx4 v[28:31], v[14:15], off offset:2048
	global_load_dwordx4 v[44:47], v196, s[0:1] offset:2048
	global_load_dwordx4 v[32:35], v[14:15], off offset:3072
	global_load_dwordx4 v[48:51], v196, s[0:1] offset:3072
	s_waitcnt vmcnt(8)
	v_add_f32_e32 v2, 0, v8
	v_add_f32_e32 v2, v2, v9
	v_add_f32_e32 v2, v2, v10
	v_add_f32_e32 v2, v2, v11
	v_add_f32_e32 v2, v2, v4
	v_add_f32_e32 v2, v2, v5
	v_add_f32_e32 v2, v2, v6
	v_add_f32_e32 v2, v2, v7
	v_fmamk_f32 v2, v2, 0x3a800000, v246
	v_cmp_gt_f32_e32 vcc, s10, v2
	v_mul_f32_e32 v4, 0x4b800000, v2
	v_lshlrev_b64 v[6:7], 12, v[12:13]
	v_cndmask_b32_e32 v2, v2, v4, vcc
	v_rsq_f32_e32 v2, v2
	v_lshl_add_u64 v[12:13], s[2:3], 0, v[6:7]
	v_mul_f32_e32 v4, 0x45800000, v2
	v_cndmask_b32_e32 v2, v2, v4, vcc
	v_lshl_add_u64 v[12:13], v[12:13], 0, v[196:197]
	s_waitcnt vmcnt(6)
	v_pk_mul_f32 v[20:21], v[20:21], v[2:3] op_sel_hi:[1,0]
	v_pk_mul_f32 v[22:23], v[22:23], v[2:3] op_sel_hi:[1,0]
	v_pk_mul_f32 v[20:21], v[36:37], v[20:21]
	v_pk_mul_f32 v[22:23], v[38:39], v[22:23]
	global_store_dwordx4 v[12:13], v[20:23], off
	s_waitcnt vmcnt(5)
	v_pk_mul_f32 v[26:27], v[2:3], v[26:27] op_sel_hi:[0,1]
	v_pk_mul_f32 v[24:25], v[2:3], v[24:25] op_sel_hi:[0,1]
	v_pk_mul_f32 v[24:25], v[24:25], v[40:41]
	v_pk_mul_f32 v[26:27], v[26:27], v[42:43]
	global_store_dwordx4 v[12:13], v[24:27], off offset:1024
	s_waitcnt vmcnt(4)
	v_pk_mul_f32 v[30:31], v[2:3], v[30:31] op_sel_hi:[0,1]
	v_pk_mul_f32 v[28:29], v[2:3], v[28:29] op_sel_hi:[0,1]
	v_pk_mul_f32 v[28:29], v[28:29], v[44:45]
	v_pk_mul_f32 v[30:31], v[30:31], v[46:47]
	global_store_dwordx4 v[12:13], v[28:31], off offset:2048
	s_waitcnt vmcnt(3)
	v_pk_mul_f32 v[34:35], v[2:3], v[34:35] op_sel_hi:[0,1]
	v_pk_mul_f32 v[32:33], v[2:3], v[32:33] op_sel_hi:[0,1]
	v_pk_mul_f32 v[32:33], v[32:33], v[48:49]
	v_pk_mul_f32 v[34:35], v[34:35], v[50:51]
	v_add_u32_e32 v3, s9, v3
	global_store_dwordx4 v[12:13], v[32:35], off offset:3072
	s_cbranch_scc0 .LBB0_56
